# attention units rebalanced: both context-attention units go to the workgroups whose retention unit is lighter
# baseline (speedup 1.0000x reference)
.LBB0_104:
	v_add_u32_e32 v30, s16, v51
	v_add_u32_e32 v31, v30, v56
	v_add_u32_e32 v29, s16, v56
	ds_read_b128 v[38:41], v31
	ds_read_b128 v[56:59], v31 offset:64
	v_add_u32_e32 v31, v29, v50
	ds_read_b128 v[60:63], v31 offset:9216
	s_waitcnt lgkmcnt(2)
	v_mfma_f32_16x16x32_bf16 v[38:41], v[38:41], v[0:3], 0
	v_add_u32_e32 v36, v29, v49
	s_lshl_b32 s2, s5, 1
	s_lshl_b32 s98, s62, 1
	s_add_i32 s98, s98, 0x100
	s_add_i32 s99, s4, 1
	s_cmpk_lt_i32 s4, 0x100
	s_cselect_b32 s99, s98, s99
	s_cselect_b32 s98, s62, 0
	s_cmpk_gt_i32 s98, 0x7f
	s_cselect_b32 s99, 0x200, s99
	s_and_b32 s98, s4, 0x101
	s_cmpk_eq_i32 s98, 0x101
	s_cselect_b32 s99, 0x200, s99
	s_add_i32 s98, s4, s34
	s_cmpk_eq_i32 s34, 0x100
	s_cselect_b32 s4, s99, s98
	s_waitcnt lgkmcnt(1)
	v_mfma_f32_16x16x32_bf16 v[38:41], v[56:59], v[4:7], v[38:41]
	s_cmpk_gt_i32 s4, 0x1ff
	s_mov_b64 s[22:23], s[44:45]
	s_waitcnt lgkmcnt(0)
	v_mfma_f32_16x16x32_bf16 v[38:41], v[60:63], v[8:11], v[38:41]
	ds_read_b128 v[48:51], v36
	ds_read_b128 v[56:59], v36 offset:64
	ds_read_b128 v[60:63], v31 offset:10496
	v_add_u32_e32 v36, v29, v47
	v_add_u32_e32 v29, v29, v46
	s_waitcnt lgkmcnt(2)
	v_mfma_f32_16x16x32_bf16 v[48:51], v[48:51], v[0:3], 0
	s_waitcnt lgkmcnt(1)
	v_mfma_f32_16x16x32_bf16 v[48:51], v[56:59], v[4:7], v[48:51]
	s_waitcnt lgkmcnt(0)
	v_mfma_f32_16x16x32_bf16 v[48:51], v[60:63], v[8:11], v[48:51]
	ds_read_b128 v[56:59], v36
	ds_read_b128 v[60:63], v36 offset:64
	ds_read_b128 v[64:67], v31 offset:11776
	s_waitcnt lgkmcnt(2)
	v_mfma_f32_16x16x32_bf16 v[56:59], v[56:59], v[0:3], 0
	s_waitcnt lgkmcnt(1)
	v_mfma_f32_16x16x32_bf16 v[56:59], v[60:63], v[4:7], v[56:59]
	s_waitcnt lgkmcnt(0)
	v_mfma_f32_16x16x32_bf16 v[56:59], v[64:67], v[8:11], v[56:59]
	ds_read_b128 v[60:63], v29
	ds_read_b128 v[64:67], v29 offset:64
	ds_read_b128 v[68:71], v31 offset:13056
	s_waitcnt lgkmcnt(2)
	v_mfma_f32_16x16x32_bf16 v[0:3], v[60:63], v[0:3], 0
	s_waitcnt lgkmcnt(1)
	v_mfma_f32_16x16x32_bf16 v[0:3], v[64:67], v[4:7], v[0:3]
	v_max_f32_e32 v6, v50, v50
	s_waitcnt lgkmcnt(0)
	v_mfma_f32_16x16x32_bf16 v[2:5], v[68:71], v[8:11], v[0:3]
	s_nop 4
	v_max_f32_e32 v0, v41, v41
	v_max_f32_e32 v1, v40, v40
	v_max_f32_e32 v0, v1, v0
	v_max_f32_e32 v1, v51, v51
	v_max_f32_e32 v1, v6, v1
	v_max3_f32 v0, v38, v39, v0
	v_max3_f32 v1, v48, v49, v1
	v_max3_f32 v0, v0, s70, v1
	v_max_f32_e32 v1, v59, v59
	v_max_f32_e32 v6, v58, v58
	v_max_f32_e32 v1, v6, v1
	v_max_f32_e32 v6, v5, v5
	v_max_f32_e32 v7, v4, v4
	v_max_f32_e32 v6, v7, v6
	v_max3_f32 v1, v56, v57, v1
	v_max3_f32 v6, v2, v3, v6
	v_max3_f32 v0, v0, v1, v6
	ds_bpermute_b32 v1, v37, v0
	s_waitcnt lgkmcnt(0)
	v_max_f32_e32 v1, v1, v1
	v_max_f32_e32 v0, v0, v1
	ds_bpermute_b32 v1, v35, v0
	s_waitcnt lgkmcnt(0)
	v_max3_f32 v1, v45, v0, v1
	v_sub_f32_e32 v6, v38, v1
	v_sub_f32_e32 v8, v48, v1
	v_exp_f32_e32 v29, v6
	v_sub_f32_e32 v6, v39, v1
	v_exp_f32_e32 v43, v8
	v_sub_f32_e32 v8, v49, v1
	v_exp_f32_e32 v31, v6
	v_sub_f32_e32 v6, v40, v1
	v_exp_f32_e32 v44, v8
	v_sub_f32_e32 v8, v50, v1
	v_sub_f32_e32 v0, v45, v1
	v_exp_f32_e32 v36, v6
	v_sub_f32_e32 v6, v41, v1
	v_exp_f32_e32 v45, v8
	v_sub_f32_e32 v8, v51, v1
	v_exp_f32_e32 v42, v6
	v_exp_f32_e32 v46, v8
	v_cvt_pk_bf16_f32 v6, v29, v31
	v_cvt_pk_bf16_f32 v8, v43, v44
	v_cvt_pk_bf16_f32 v7, v36, v42
	v_cvt_pk_bf16_f32 v9, v45, v46
	ds_write2_b64 v52, v[6:7], v[8:9] offset1:4
	v_sub_f32_e32 v6, v56, v1
	v_exp_f32_e32 v47, v6
	v_sub_f32_e32 v6, v57, v1
	v_sub_f32_e32 v2, v2, v1
	v_exp_f32_e32 v48, v6
	v_sub_f32_e32 v6, v58, v1
	v_exp_f32_e32 v51, v2
	v_sub_f32_e32 v2, v3, v1
	v_exp_f32_e32 v49, v6
	v_sub_f32_e32 v6, v59, v1
	v_exp_f32_e32 v53, v2
	v_sub_f32_e32 v2, v4, v1
	v_sub_f32_e32 v1, v5, v1
	v_exp_f32_e32 v50, v6
	v_exp_f32_e32 v54, v2
	v_exp_f32_e32 v1, v1
	v_exp_f32_e32 v0, v0
	v_cvt_pk_bf16_f32 v6, v47, v48
	v_cvt_pk_bf16_f32 v7, v49, v50
	v_cvt_pk_bf16_f32 v2, v51, v53
	v_cvt_pk_bf16_f32 v3, v54, v1
	ds_write2_b64 v52, v[6:7], v[2:3] offset0:8 offset1:12
	v_pk_mul_f32 v[6:7], v[16:17], v[0:1] op_sel_hi:[1,0]
	v_pk_mul_f32 v[16:17], v[26:27], v[0:1] op_sel_hi:[1,0]
	v_add_u32_e32 v26, v30, v152
	v_pk_mul_f32 v[4:5], v[14:15], v[0:1] op_sel_hi:[1,0]
	v_pk_mul_f32 v[2:3], v[12:13], v[0:1] op_sel_hi:[1,0]
	v_pk_mul_f32 v[8:9], v[18:19], v[0:1] op_sel_hi:[1,0]
	v_pk_mul_f32 v[12:13], v[22:23], v[0:1] op_sel_hi:[1,0]
	v_pk_mul_f32 v[10:11], v[20:21], v[0:1] op_sel_hi:[1,0]
	v_pk_mul_f32 v[14:15], v[24:25], v[0:1] op_sel_hi:[1,0]
	ds_read_b128 v[18:21], v55 offset:47104
	ds_read_b128 v[22:25], v55 offset:47168
	ds_read_b128 v[38:41], v26 offset:14336
	s_waitcnt lgkmcnt(0)
	v_mfma_f32_16x16x32_bf16 v[2:5], v[38:41], v[18:21], v[2:5]
	ds_read_b128 v[38:41], v26 offset:14400
	s_waitcnt lgkmcnt(0)
	v_mfma_f32_16x16x32_bf16 v[2:5], v[38:41], v[22:25], v[2:5]
	ds_read_b128 v[38:41], v26 offset:16640
	s_waitcnt lgkmcnt(0)
	v_mfma_f32_16x16x32_bf16 v[6:9], v[38:41], v[18:21], v[6:9]
	ds_read_b128 v[38:41], v26 offset:16704
	s_waitcnt lgkmcnt(0)
	v_mfma_f32_16x16x32_bf16 v[6:9], v[38:41], v[22:25], v[6:9]
	ds_read_b128 v[38:41], v26 offset:18944
	s_waitcnt lgkmcnt(0)
	v_mfma_f32_16x16x32_bf16 v[10:13], v[38:41], v[18:21], v[10:13]
	ds_read_b128 v[38:41], v26 offset:19008
	s_waitcnt lgkmcnt(0)
	v_mfma_f32_16x16x32_bf16 v[10:13], v[38:41], v[22:25], v[10:13]
	ds_read_b128 v[38:41], v26 offset:21248
	s_waitcnt lgkmcnt(0)
	v_mfma_f32_16x16x32_bf16 v[14:17], v[38:41], v[18:21], v[14:17]
	ds_read_b128 v[18:21], v26 offset:21312
	s_waitcnt lgkmcnt(0)
	s_barrier
	v_mfma_f32_16x16x32_bf16 v[14:17], v[18:21], v[22:25], v[14:17]
	v_add_f32_e32 v18, 0, v29
	v_add_f32_e32 v18, v31, v18
	v_add_f32_e32 v18, v36, v18
	v_add_f32_e32 v18, v42, v18
	v_add_f32_e32 v18, v43, v18
	v_add_f32_e32 v18, v44, v18
	v_add_f32_e32 v18, v45, v18
	v_add_f32_e32 v18, v46, v18
	v_add_f32_e32 v18, v47, v18
	v_add_f32_e32 v18, v48, v18
	v_add_f32_e32 v18, v49, v18
	v_add_f32_e32 v18, v50, v18
	v_add_f32_e32 v18, v51, v18
	v_add_f32_e32 v18, v53, v18
	v_add_f32_e32 v18, v54, v18
	v_add_f32_e32 v1, v1, v18
	v_fmac_f32_e32 v1, v28, v0
	ds_bpermute_b32 v0, v37, v1
	s_waitcnt lgkmcnt(0)
	v_add_f32_e32 v0, v1, v0
	ds_bpermute_b32 v1, v35, v0
	v_mov_b32_e32 v35, v153
	s_waitcnt lgkmcnt(0)
	v_add_f32_e32 v0, v0, v1
	v_div_scale_f32 v1, s[8:9], v0, v0, 1.0
	v_rcp_f32_e32 v18, v1
	s_nop 0
	v_fma_f32 v19, -v1, v18, 1.0
	v_fmac_f32_e32 v18, v19, v18
	v_div_scale_f32 v19, vcc, 1.0, v0, 1.0
	v_mul_f32_e32 v20, v19, v18
	v_fma_f32 v21, -v1, v20, v19
	v_fmac_f32_e32 v20, v21, v18
	v_fma_f32 v1, -v1, v20, v19
	v_div_fmas_f32 v1, v1, v18, v20
	v_div_fixup_f32 v0, v1, v0, 1.0
	v_lshlrev_b64 v[18:19], 12, v[32:33]
	v_pk_mul_f32 v[4:5], v[4:5], v[0:1] op_sel_hi:[1,0]
	v_pk_mul_f32 v[2:3], v[2:3], v[0:1] op_sel_hi:[1,0]
	v_pk_mul_f32 v[6:7], v[6:7], v[0:1] op_sel_hi:[1,0]
	v_cvt_pk_bf16_f32 v2, v2, v3
	v_cvt_pk_bf16_f32 v3, v4, v5
	v_lshl_add_u64 v[4:5], s[18:19], 0, v[18:19]
	v_lshl_add_u64 v[4:5], v[4:5], 0, s[2:3]
	v_lshl_add_u64 v[4:5], v[4:5], 0, v[34:35]
	s_mov_b32 s2, 0x7f00000
	v_add_co_u32_e32 v4, vcc, s2, v4
	v_cvt_pk_bf16_f32 v6, v6, v7
	s_nop 0
	v_addc_co_u32_e32 v5, vcc, 0, v5, vcc
	flat_store_dwordx2 v[4:5], v[2:3] offset:3072
	v_pk_mul_f32 v[2:3], v[8:9], v[0:1] op_sel_hi:[1,0]
	s_nop 0
	v_cvt_pk_bf16_f32 v7, v2, v3
	flat_store_dwordx2 v[4:5], v[6:7] offset:3104
	v_pk_mul_f32 v[2:3], v[12:13], v[0:1] op_sel_hi:[1,0]
	v_pk_mul_f32 v[6:7], v[10:11], v[0:1] op_sel_hi:[1,0]
	s_nop 0
	v_cvt_pk_bf16_f32 v6, v6, v7
	v_cvt_pk_bf16_f32 v7, v2, v3
	v_pk_mul_f32 v[2:3], v[16:17], v[0:1] op_sel_hi:[1,0]
	v_pk_mul_f32 v[0:1], v[14:15], v[0:1] op_sel_hi:[1,0]
	flat_store_dwordx2 v[4:5], v[6:7] offset:3136
	v_cvt_pk_bf16_f32 v0, v0, v1
	v_cvt_pk_bf16_f32 v1, v2, v3
	flat_store_dwordx2 v[4:5], v[0:1] offset:3168
	s_cbranch_scc1 .LBB0_116
